# v71 + conv epilogue 1/sqrt sequences: removed tiny-input rescale and inf/zero class handling that cannot trigger (x >= 1e-6)
# speedup vs baseline: 1.0068x; 1.0002x over previous
.LBB0_1133:
	s_mul_hi_i32 s0, s22, 0x3e0f83e1
	s_lshr_b32 s1, s0, 31
	s_ashr_i32 s0, s0, 3
	s_add_i32 s0, s0, s1
	s_mul_i32 s1, s0, 0xffffffdf
	s_add_i32 s1, s1, s22
	s_mul_i32 s18, s1, 0xfe
	s_add_i32 s18, s18, -2
	v_add_u32_e32 v197, s18, v177
	s_lshl_b32 s33, s0, 13
	v_readlane_b32 s100, v249, 28
	v_readlane_b32 s101, v249, 29
	v_mov_b32_e32 v252, v197
	v_cmp_gt_u32_e32 vcc, s73, v252
	s_and_saveexec_b64 s[98:99], vcc
	v_or_b32_e32 v252, s33, v252
	v_ashrrev_i32_e32 v253, 31, v252
	v_lshl_add_u64 v[252:253], v[252:253], 2, s[100:101]
	global_load_dword v242, v[252:253], off
	s_mov_b64 exec, s[98:99]
	v_add_u32_e32 v252, 16, v197
	v_cmp_gt_u32_e32 vcc, s73, v252
	s_and_saveexec_b64 s[98:99], vcc
	v_or_b32_e32 v252, s33, v252
	v_ashrrev_i32_e32 v253, 31, v252
	v_lshl_add_u64 v[252:253], v[252:253], 2, s[100:101]
	global_load_dword v243, v[252:253], off
	s_mov_b64 exec, s[98:99]
	v_add_u32_e32 v252, 32, v197
	v_cmp_gt_u32_e32 vcc, s73, v252
	s_and_saveexec_b64 s[98:99], vcc
	v_or_b32_e32 v252, s33, v252
	v_ashrrev_i32_e32 v253, 31, v252
	v_lshl_add_u64 v[252:253], v[252:253], 2, s[100:101]
	global_load_dword v244, v[252:253], off
	s_mov_b64 exec, s[98:99]
	v_add_u32_e32 v252, 48, v197
	v_cmp_gt_u32_e32 vcc, s73, v252
	s_and_saveexec_b64 s[98:99], vcc
	v_or_b32_e32 v252, s33, v252
	v_ashrrev_i32_e32 v253, 31, v252
	v_lshl_add_u64 v[252:253], v[252:253], 2, s[100:101]
	global_load_dword v245, v[252:253], off
	s_mov_b64 exec, s[98:99]
	v_add_u32_e32 v252, 128, v197
	v_cmp_gt_u32_e32 vcc, s73, v252
	s_and_saveexec_b64 s[98:99], vcc
	v_or_b32_e32 v252, s33, v252
	v_ashrrev_i32_e32 v253, 31, v252
	v_lshl_add_u64 v[252:253], v[252:253], 2, s[100:101]
	global_load_dword v246, v[252:253], off
	s_mov_b64 exec, s[98:99]
	v_add_u32_e32 v252, 144, v197
	v_cmp_gt_u32_e32 vcc, s73, v252
	s_and_saveexec_b64 s[98:99], vcc
	v_or_b32_e32 v252, s33, v252
	v_ashrrev_i32_e32 v253, 31, v252
	v_lshl_add_u64 v[252:253], v[252:253], 2, s[100:101]
	global_load_dword v247, v[252:253], off
	s_mov_b64 exec, s[98:99]
	v_add_u32_e32 v252, 160, v197
	v_cmp_gt_u32_e32 vcc, s73, v252
	s_and_saveexec_b64 s[98:99], vcc
	v_or_b32_e32 v252, s33, v252
	v_ashrrev_i32_e32 v253, 31, v252
	v_lshl_add_u64 v[252:253], v[252:253], 2, s[100:101]
	global_load_dword v250, v[252:253], off
	s_mov_b64 exec, s[98:99]
	v_add_u32_e32 v252, 176, v197
	v_cmp_gt_u32_e32 vcc, s73, v252
	s_and_saveexec_b64 s[98:99], vcc
	v_or_b32_e32 v252, s33, v252
	v_ashrrev_i32_e32 v253, 31, v252
	v_lshl_add_u64 v[252:253], v[252:253], 2, s[100:101]
	global_load_dword v251, v[252:253], off
	s_mov_b64 exec, s[98:99]
	v_cmp_gt_u32_e32 vcc, s73, v197
	v_mov_b32_e32 v202, 0
	v_mov_b32_e32 v204, 0
	s_and_saveexec_b64 s[14:15], vcc
	s_cbranch_execz .LBB0_1135
	v_or_b32_e32 v100, s33, v197
	v_readlane_b32 s0, v249, 28
	v_ashrrev_i32_e32 v101, 31, v100
	v_readlane_b32 s1, v249, 29
	s_nop 1
	v_lshl_add_u64 v[100:101], v[100:101], 2, s[0:1]
	s_waitcnt vmcnt(0)
	v_mov_b32_e32 v100, v242
	v_fmamk_f32 v100, v100, 0x3a800000, v237
	v_sqrt_f32_e32 v101, v100
	s_nop 0
	v_add_u32_e32 v102, -1, v101
	v_add_u32_e32 v103, 1, v101
	v_fma_f32 v104, -v102, v101, v100
	v_fma_f32 v105, -v103, v101, v100
	v_cmp_ge_f32_e64 s[0:1], 0, v104
	s_nop 1
	v_cndmask_b32_e64 v101, v101, v102, s[0:1]
	v_cmp_lt_f32_e64 s[0:1], 0, v105
	s_nop 1
	v_cndmask_b32_e64 v101, v101, v103, s[0:1]
	v_mov_b32_e32 v100, v101
	v_div_scale_f32 v101, s[0:1], v100, v100, 1.0
	v_rcp_f32_e32 v102, v101
	v_div_scale_f32 v103, vcc, 1.0, v100, 1.0
	v_fma_f32 v104, -v101, v102, 1.0
	v_fmac_f32_e32 v102, v104, v102
	v_mul_f32_e32 v104, v103, v102
	v_fma_f32 v105, -v101, v104, v103
	v_fmac_f32_e32 v104, v105, v102
	v_fma_f32 v101, -v101, v104, v103
	v_div_fmas_f32 v101, v101, v102, v104
	v_div_fixup_f32 v204, v101, v100, 1.0
.LBB0_1135:
	s_or_b64 exec, exec, s[14:15]
	v_add_u32_e32 v100, 16, v197
	v_cmp_gt_u32_e32 vcc, s73, v100
	s_and_saveexec_b64 s[14:15], vcc
	s_cbranch_execz .LBB0_1137
	v_or_b32_e32 v100, s33, v100
	v_readlane_b32 s0, v249, 28
	v_ashrrev_i32_e32 v101, 31, v100
	v_readlane_b32 s1, v249, 29
	s_nop 1
	v_lshl_add_u64 v[100:101], v[100:101], 2, s[0:1]
	s_waitcnt vmcnt(0)
	v_mov_b32_e32 v100, v243
	v_fmamk_f32 v100, v100, 0x3a800000, v237
	v_sqrt_f32_e32 v101, v100
	s_nop 0
	v_add_u32_e32 v102, -1, v101
	v_add_u32_e32 v103, 1, v101
	v_fma_f32 v104, -v102, v101, v100
	v_fma_f32 v105, -v103, v101, v100
	v_cmp_ge_f32_e64 s[0:1], 0, v104
	s_nop 1
	v_cndmask_b32_e64 v101, v101, v102, s[0:1]
	v_cmp_lt_f32_e64 s[0:1], 0, v105
	s_nop 1
	v_cndmask_b32_e64 v101, v101, v103, s[0:1]
	v_mov_b32_e32 v100, v101
	v_div_scale_f32 v101, s[0:1], v100, v100, 1.0
	v_rcp_f32_e32 v102, v101
	v_div_scale_f32 v103, vcc, 1.0, v100, 1.0
	v_fma_f32 v104, -v101, v102, 1.0
	v_fmac_f32_e32 v102, v104, v102
	v_mul_f32_e32 v104, v103, v102
	v_fma_f32 v105, -v101, v104, v103
	v_fmac_f32_e32 v104, v105, v102
	v_fma_f32 v101, -v101, v104, v103
	v_div_fmas_f32 v101, v101, v102, v104
	v_div_fixup_f32 v202, v101, v100, 1.0
.LBB0_1137:
	s_or_b64 exec, exec, s[14:15]
	v_add_u32_e32 v100, 32, v197
	v_cmp_gt_u32_e32 vcc, s73, v100
	v_mov_b32_e32 v128, 0
	v_mov_b32_e32 v200, 0
	s_and_saveexec_b64 s[14:15], vcc
	s_cbranch_execz .LBB0_1139
	v_or_b32_e32 v100, s33, v100
	v_readlane_b32 s0, v249, 28
	v_ashrrev_i32_e32 v101, 31, v100
	v_readlane_b32 s1, v249, 29
	s_nop 1
	v_lshl_add_u64 v[100:101], v[100:101], 2, s[0:1]
	s_waitcnt vmcnt(0)
	v_mov_b32_e32 v100, v244
	v_fmamk_f32 v100, v100, 0x3a800000, v237
	v_sqrt_f32_e32 v101, v100
	s_nop 0
	v_add_u32_e32 v102, -1, v101
	v_add_u32_e32 v103, 1, v101
	v_fma_f32 v104, -v102, v101, v100
	v_fma_f32 v105, -v103, v101, v100
	v_cmp_ge_f32_e64 s[0:1], 0, v104
	s_nop 1
	v_cndmask_b32_e64 v101, v101, v102, s[0:1]
	v_cmp_lt_f32_e64 s[0:1], 0, v105
	s_nop 1
	v_cndmask_b32_e64 v101, v101, v103, s[0:1]
	v_mov_b32_e32 v100, v101
	v_div_scale_f32 v101, s[0:1], v100, v100, 1.0
	v_rcp_f32_e32 v102, v101
	v_div_scale_f32 v103, vcc, 1.0, v100, 1.0
	v_fma_f32 v104, -v101, v102, 1.0
	v_fmac_f32_e32 v102, v104, v102
	v_mul_f32_e32 v104, v103, v102
	v_fma_f32 v105, -v101, v104, v103
	v_fmac_f32_e32 v104, v105, v102
	v_fma_f32 v101, -v101, v104, v103
	v_div_fmas_f32 v101, v101, v102, v104
	v_div_fixup_f32 v200, v101, v100, 1.0
.LBB0_1139:
	s_or_b64 exec, exec, s[14:15]
	v_add_u32_e32 v100, 48, v197
	v_cmp_gt_u32_e32 vcc, s73, v100
	s_and_saveexec_b64 s[14:15], vcc
	s_cbranch_execz .LBB0_1141
	v_or_b32_e32 v100, s33, v100
	v_readlane_b32 s0, v249, 28
	v_ashrrev_i32_e32 v101, 31, v100
	v_readlane_b32 s1, v249, 29
	s_nop 1
	v_lshl_add_u64 v[100:101], v[100:101], 2, s[0:1]
	s_waitcnt vmcnt(0)
	v_mov_b32_e32 v100, v245
	v_fmamk_f32 v100, v100, 0x3a800000, v237
	v_sqrt_f32_e32 v101, v100
	s_nop 0
	v_add_u32_e32 v102, -1, v101
	v_add_u32_e32 v103, 1, v101
	v_fma_f32 v104, -v102, v101, v100
	v_fma_f32 v105, -v103, v101, v100
	v_cmp_ge_f32_e64 s[0:1], 0, v104
	s_nop 1
	v_cndmask_b32_e64 v101, v101, v102, s[0:1]
	v_cmp_lt_f32_e64 s[0:1], 0, v105
	s_nop 1
	v_cndmask_b32_e64 v101, v101, v103, s[0:1]
	v_mov_b32_e32 v100, v101
	v_div_scale_f32 v101, s[0:1], v100, v100, 1.0
	v_rcp_f32_e32 v102, v101
	v_div_scale_f32 v103, vcc, 1.0, v100, 1.0
	v_fma_f32 v104, -v101, v102, 1.0
	v_fmac_f32_e32 v102, v104, v102
	v_mul_f32_e32 v104, v103, v102
	v_fma_f32 v105, -v101, v104, v103
	v_fmac_f32_e32 v104, v105, v102
	v_fma_f32 v101, -v101, v104, v103
	v_div_fmas_f32 v101, v101, v102, v104
	v_div_fixup_f32 v128, v101, v100, 1.0
.LBB0_1141:
	s_or_b64 exec, exec, s[14:15]
	v_add_u32_e32 v241, 0x80, v197
	v_cmp_gt_u32_e32 vcc, s73, v241
	v_mov_b32_e32 v196, 0
	v_mov_b32_e32 v198, 0
	s_and_saveexec_b64 s[14:15], vcc
	s_cbranch_execz .LBB0_1143
	v_or_b32_e32 v100, s33, v241
	v_readlane_b32 s0, v249, 28
	v_ashrrev_i32_e32 v101, 31, v100
	v_readlane_b32 s1, v249, 29
	s_nop 1
	v_lshl_add_u64 v[100:101], v[100:101], 2, s[0:1]
	s_waitcnt vmcnt(0)
	v_mov_b32_e32 v100, v246
	v_fmamk_f32 v100, v100, 0x3a800000, v237
	v_sqrt_f32_e32 v101, v100
	s_nop 0
	v_add_u32_e32 v102, -1, v101
	v_add_u32_e32 v103, 1, v101
	v_fma_f32 v104, -v102, v101, v100
	v_fma_f32 v105, -v103, v101, v100
	v_cmp_ge_f32_e64 s[0:1], 0, v104
	s_nop 1
	v_cndmask_b32_e64 v101, v101, v102, s[0:1]
	v_cmp_lt_f32_e64 s[0:1], 0, v105
	s_nop 1
	v_cndmask_b32_e64 v101, v101, v103, s[0:1]
	v_mov_b32_e32 v100, v101
	v_div_scale_f32 v101, s[0:1], v100, v100, 1.0
	v_rcp_f32_e32 v102, v101
	v_div_scale_f32 v103, vcc, 1.0, v100, 1.0
	v_fma_f32 v104, -v101, v102, 1.0
	v_fmac_f32_e32 v102, v104, v102
	v_mul_f32_e32 v104, v103, v102
	v_fma_f32 v105, -v101, v104, v103
	v_fmac_f32_e32 v104, v105, v102
	v_fma_f32 v101, -v101, v104, v103
	v_div_fmas_f32 v101, v101, v102, v104
	v_div_fixup_f32 v198, v101, v100, 1.0
.LBB0_1143:
	s_or_b64 exec, exec, s[14:15]
	v_add_u32_e32 v240, 0x90, v197
	v_cmp_gt_u32_e32 vcc, s73, v240
	s_and_saveexec_b64 s[14:15], vcc
	s_cbranch_execz .LBB0_1145
	v_or_b32_e32 v100, s33, v240
	v_readlane_b32 s0, v249, 28
	v_ashrrev_i32_e32 v101, 31, v100
	v_readlane_b32 s1, v249, 29
	s_nop 1
	v_lshl_add_u64 v[100:101], v[100:101], 2, s[0:1]
	s_waitcnt vmcnt(0)
	v_mov_b32_e32 v100, v247
	v_fmamk_f32 v100, v100, 0x3a800000, v237
	v_sqrt_f32_e32 v101, v100
	s_nop 0
	v_add_u32_e32 v102, -1, v101
	v_add_u32_e32 v103, 1, v101
	v_fma_f32 v104, -v102, v101, v100
	v_fma_f32 v105, -v103, v101, v100
	v_cmp_ge_f32_e64 s[0:1], 0, v104
	s_nop 1
	v_cndmask_b32_e64 v101, v101, v102, s[0:1]
	v_cmp_lt_f32_e64 s[0:1], 0, v105
	s_nop 1
	v_cndmask_b32_e64 v101, v101, v103, s[0:1]
	v_mov_b32_e32 v100, v101
	v_div_scale_f32 v101, s[0:1], v100, v100, 1.0
	v_rcp_f32_e32 v102, v101
	v_div_scale_f32 v103, vcc, 1.0, v100, 1.0
	v_fma_f32 v104, -v101, v102, 1.0
	v_fmac_f32_e32 v102, v104, v102
	v_mul_f32_e32 v104, v103, v102
	v_fma_f32 v105, -v101, v104, v103
	v_fmac_f32_e32 v104, v105, v102
	v_fma_f32 v101, -v101, v104, v103
	v_div_fmas_f32 v101, v101, v102, v104
	v_div_fixup_f32 v196, v101, v100, 1.0
.LBB0_1145:
	s_or_b64 exec, exec, s[14:15]
	v_add_u32_e32 v205, 0xa0, v197
	v_cmp_gt_u32_e32 vcc, s73, v205
	v_mov_b32_e32 v130, 0
	v_mov_b32_e32 v194, 0
	s_and_saveexec_b64 s[14:15], vcc
	s_cbranch_execz .LBB0_1147
	v_or_b32_e32 v100, s33, v205
	v_readlane_b32 s0, v249, 28
	v_ashrrev_i32_e32 v101, 31, v100
	v_readlane_b32 s1, v249, 29
	s_nop 1
	v_lshl_add_u64 v[100:101], v[100:101], 2, s[0:1]
	s_waitcnt vmcnt(0)
	v_mov_b32_e32 v100, v250
	v_fmamk_f32 v100, v100, 0x3a800000, v237
	v_sqrt_f32_e32 v101, v100
	s_nop 0
	v_add_u32_e32 v102, -1, v101
	v_add_u32_e32 v103, 1, v101
	v_fma_f32 v104, -v102, v101, v100
	v_fma_f32 v105, -v103, v101, v100
	v_cmp_ge_f32_e64 s[0:1], 0, v104
	s_nop 1
	v_cndmask_b32_e64 v101, v101, v102, s[0:1]
	v_cmp_lt_f32_e64 s[0:1], 0, v105
	s_nop 1
	v_cndmask_b32_e64 v101, v101, v103, s[0:1]
	v_mov_b32_e32 v100, v101
	v_div_scale_f32 v101, s[0:1], v100, v100, 1.0
	v_rcp_f32_e32 v102, v101
	v_div_scale_f32 v103, vcc, 1.0, v100, 1.0
	v_fma_f32 v104, -v101, v102, 1.0
	v_fmac_f32_e32 v102, v104, v102
	v_mul_f32_e32 v104, v103, v102
	v_fma_f32 v105, -v101, v104, v103
	v_fmac_f32_e32 v104, v105, v102
	v_fma_f32 v101, -v101, v104, v103
	v_div_fmas_f32 v101, v101, v102, v104
	v_div_fixup_f32 v194, v101, v100, 1.0
.LBB0_1147:
	s_or_b64 exec, exec, s[14:15]
	v_add_u32_e32 v203, 0xb0, v197
	v_cmp_gt_u32_e32 vcc, s73, v203
	s_and_saveexec_b64 s[14:15], vcc
	s_cbranch_execz .LBB0_1149
	v_or_b32_e32 v100, s33, v203
	v_readlane_b32 s0, v249, 28
	v_ashrrev_i32_e32 v101, 31, v100
	v_readlane_b32 s1, v249, 29
	s_nop 1
	v_lshl_add_u64 v[100:101], v[100:101], 2, s[0:1]
	s_waitcnt vmcnt(0)
	v_mov_b32_e32 v100, v251
	v_fmamk_f32 v100, v100, 0x3a800000, v237
	v_sqrt_f32_e32 v101, v100
	s_nop 0
	v_add_u32_e32 v102, -1, v101
	v_add_u32_e32 v103, 1, v101
	v_fma_f32 v104, -v102, v101, v100
	v_fma_f32 v105, -v103, v101, v100
	v_cmp_ge_f32_e64 s[0:1], 0, v104
	s_nop 1
	v_cndmask_b32_e64 v101, v101, v102, s[0:1]
	v_cmp_lt_f32_e64 s[0:1], 0, v105
	s_nop 1
	v_cndmask_b32_e64 v101, v101, v103, s[0:1]
	v_mov_b32_e32 v100, v101
	v_div_scale_f32 v101, s[0:1], v100, v100, 1.0
	v_rcp_f32_e32 v102, v101
	v_div_scale_f32 v103, vcc, 1.0, v100, 1.0
	v_fma_f32 v104, -v101, v102, 1.0
	v_fmac_f32_e32 v102, v104, v102
	v_mul_f32_e32 v104, v103, v102
	v_fma_f32 v105, -v101, v104, v103
	v_fmac_f32_e32 v104, v105, v102
	v_fma_f32 v101, -v101, v104, v103
	v_div_fmas_f32 v101, v101, v102, v104
	v_div_fixup_f32 v130, v101, v100, 1.0

.LBB0_2236:
	s_mul_hi_i32 s0, s22, 0x3e0f83e1
	s_lshr_b32 s1, s0, 31
	s_ashr_i32 s0, s0, 3
	s_add_i32 s0, s0, s1
	s_mul_i32 s1, s0, 0xffffffdf
	s_add_i32 s1, s1, s22
	s_mul_i32 s18, s1, 0xfe
	s_add_i32 s18, s18, -2
	v_add_u32_e32 v195, s18, v177
	s_lshl_b32 s33, s0, 13
	v_mov_b32_e32 v252, v195
	v_cmp_gt_u32_e32 vcc, s79, v252
	s_and_saveexec_b64 s[98:99], vcc
	v_or_b32_e32 v252, s33, v252
	v_ashrrev_i32_e32 v253, 31, v252
	v_lshl_add_u64 v[252:253], v[252:253], 2, s[28:29]
	global_load_dword v242, v[252:253], off
	s_mov_b64 exec, s[98:99]
	v_add_u32_e32 v252, 16, v195
	v_cmp_gt_u32_e32 vcc, s79, v252
	s_and_saveexec_b64 s[98:99], vcc
	v_or_b32_e32 v252, s33, v252
	v_ashrrev_i32_e32 v253, 31, v252
	v_lshl_add_u64 v[252:253], v[252:253], 2, s[28:29]
	global_load_dword v243, v[252:253], off
	s_mov_b64 exec, s[98:99]
	v_add_u32_e32 v252, 32, v195
	v_cmp_gt_u32_e32 vcc, s79, v252
	s_and_saveexec_b64 s[98:99], vcc
	v_or_b32_e32 v252, s33, v252
	v_ashrrev_i32_e32 v253, 31, v252
	v_lshl_add_u64 v[252:253], v[252:253], 2, s[28:29]
	global_load_dword v244, v[252:253], off
	s_mov_b64 exec, s[98:99]
	v_add_u32_e32 v252, 48, v195
	v_cmp_gt_u32_e32 vcc, s79, v252
	s_and_saveexec_b64 s[98:99], vcc
	v_or_b32_e32 v252, s33, v252
	v_ashrrev_i32_e32 v253, 31, v252
	v_lshl_add_u64 v[252:253], v[252:253], 2, s[28:29]
	global_load_dword v245, v[252:253], off
	s_mov_b64 exec, s[98:99]
	v_add_u32_e32 v252, 128, v195
	v_cmp_gt_u32_e32 vcc, s79, v252
	s_and_saveexec_b64 s[98:99], vcc
	v_or_b32_e32 v252, s33, v252
	v_ashrrev_i32_e32 v253, 31, v252
	v_lshl_add_u64 v[252:253], v[252:253], 2, s[28:29]
	global_load_dword v246, v[252:253], off
	s_mov_b64 exec, s[98:99]
	v_add_u32_e32 v252, 144, v195
	v_cmp_gt_u32_e32 vcc, s79, v252
	s_and_saveexec_b64 s[98:99], vcc
	v_or_b32_e32 v252, s33, v252
	v_ashrrev_i32_e32 v253, 31, v252
	v_lshl_add_u64 v[252:253], v[252:253], 2, s[28:29]
	global_load_dword v247, v[252:253], off
	s_mov_b64 exec, s[98:99]
	v_add_u32_e32 v252, 160, v195
	v_cmp_gt_u32_e32 vcc, s79, v252
	s_and_saveexec_b64 s[98:99], vcc
	v_or_b32_e32 v252, s33, v252
	v_ashrrev_i32_e32 v253, 31, v252
	v_lshl_add_u64 v[252:253], v[252:253], 2, s[28:29]
	global_load_dword v250, v[252:253], off
	s_mov_b64 exec, s[98:99]
	v_add_u32_e32 v252, 176, v195
	v_cmp_gt_u32_e32 vcc, s79, v252
	s_and_saveexec_b64 s[98:99], vcc
	v_or_b32_e32 v252, s33, v252
	v_ashrrev_i32_e32 v253, 31, v252
	v_lshl_add_u64 v[252:253], v[252:253], 2, s[28:29]
	global_load_dword v251, v[252:253], off
	s_mov_b64 exec, s[98:99]
	v_cmp_gt_u32_e32 vcc, s79, v195
	v_mov_b32_e32 v200, 0
	v_mov_b32_e32 v202, 0
	s_and_saveexec_b64 s[14:15], vcc
	s_cbranch_execz .LBB0_2238
	v_or_b32_e32 v96, s33, v195
	v_ashrrev_i32_e32 v97, 31, v96
	v_lshl_add_u64 v[96:97], v[96:97], 2, s[28:29]
	s_waitcnt vmcnt(0)
	v_mov_b32_e32 v96, v242
	v_fmamk_f32 v96, v96, 0x3a800000, v237
	v_sqrt_f32_e32 v97, v96
	s_nop 0
	v_add_u32_e32 v98, -1, v97
	v_add_u32_e32 v99, 1, v97
	v_fma_f32 v100, -v98, v97, v96
	v_fma_f32 v101, -v99, v97, v96
	v_cmp_ge_f32_e64 s[0:1], 0, v100
	s_nop 1
	v_cndmask_b32_e64 v97, v97, v98, s[0:1]
	v_cmp_lt_f32_e64 s[0:1], 0, v101
	s_nop 1
	v_cndmask_b32_e64 v97, v97, v99, s[0:1]
	v_mov_b32_e32 v96, v97
	v_div_scale_f32 v97, s[0:1], v96, v96, 1.0
	v_rcp_f32_e32 v98, v97
	v_div_scale_f32 v99, vcc, 1.0, v96, 1.0
	v_fma_f32 v100, -v97, v98, 1.0
	v_fmac_f32_e32 v98, v100, v98
	v_mul_f32_e32 v100, v99, v98
	v_fma_f32 v101, -v97, v100, v99
	v_fmac_f32_e32 v100, v101, v98
	v_fma_f32 v97, -v97, v100, v99
	v_div_fmas_f32 v97, v97, v98, v100
	v_div_fixup_f32 v202, v97, v96, 1.0
.LBB0_2238:
	s_or_b64 exec, exec, s[14:15]
	v_add_u32_e32 v96, 16, v195
	v_cmp_gt_u32_e32 vcc, s79, v96
	s_and_saveexec_b64 s[14:15], vcc
	s_cbranch_execz .LBB0_2240
	v_or_b32_e32 v96, s33, v96
	v_ashrrev_i32_e32 v97, 31, v96
	v_lshl_add_u64 v[96:97], v[96:97], 2, s[28:29]
	s_waitcnt vmcnt(0)
	v_mov_b32_e32 v96, v243
	v_fmamk_f32 v96, v96, 0x3a800000, v237
	v_sqrt_f32_e32 v97, v96
	s_nop 0
	v_add_u32_e32 v98, -1, v97
	v_add_u32_e32 v99, 1, v97
	v_fma_f32 v100, -v98, v97, v96
	v_fma_f32 v101, -v99, v97, v96
	v_cmp_ge_f32_e64 s[0:1], 0, v100
	s_nop 1
	v_cndmask_b32_e64 v97, v97, v98, s[0:1]
	v_cmp_lt_f32_e64 s[0:1], 0, v101
	s_nop 1
	v_cndmask_b32_e64 v97, v97, v99, s[0:1]
	v_mov_b32_e32 v96, v97
	v_div_scale_f32 v97, s[0:1], v96, v96, 1.0
	v_rcp_f32_e32 v98, v97
	v_div_scale_f32 v99, vcc, 1.0, v96, 1.0
	v_fma_f32 v100, -v97, v98, 1.0
	v_fmac_f32_e32 v98, v100, v98
	v_mul_f32_e32 v100, v99, v98
	v_fma_f32 v101, -v97, v100, v99
	v_fmac_f32_e32 v100, v101, v98
	v_fma_f32 v97, -v97, v100, v99
	v_div_fmas_f32 v97, v97, v98, v100
	v_div_fixup_f32 v200, v97, v96, 1.0
.LBB0_2240:
	s_or_b64 exec, exec, s[14:15]
	v_add_u32_e32 v96, 32, v195
	v_cmp_gt_u32_e32 vcc, s79, v96
	v_mov_b32_e32 v128, 0
	v_mov_b32_e32 v198, 0
	s_and_saveexec_b64 s[14:15], vcc
	s_cbranch_execz .LBB0_2242
	v_or_b32_e32 v96, s33, v96
	v_ashrrev_i32_e32 v97, 31, v96
	v_lshl_add_u64 v[96:97], v[96:97], 2, s[28:29]
	s_waitcnt vmcnt(0)
	v_mov_b32_e32 v96, v244
	v_fmamk_f32 v96, v96, 0x3a800000, v237
	v_sqrt_f32_e32 v97, v96
	s_nop 0
	v_add_u32_e32 v98, -1, v97
	v_add_u32_e32 v99, 1, v97
	v_fma_f32 v100, -v98, v97, v96
	v_fma_f32 v101, -v99, v97, v96
	v_cmp_ge_f32_e64 s[0:1], 0, v100
	s_nop 1
	v_cndmask_b32_e64 v97, v97, v98, s[0:1]
	v_cmp_lt_f32_e64 s[0:1], 0, v101
	s_nop 1
	v_cndmask_b32_e64 v97, v97, v99, s[0:1]
	v_mov_b32_e32 v96, v97
	v_div_scale_f32 v97, s[0:1], v96, v96, 1.0
	v_rcp_f32_e32 v98, v97
	v_div_scale_f32 v99, vcc, 1.0, v96, 1.0
	v_fma_f32 v100, -v97, v98, 1.0
	v_fmac_f32_e32 v98, v100, v98
	v_mul_f32_e32 v100, v99, v98
	v_fma_f32 v101, -v97, v100, v99
	v_fmac_f32_e32 v100, v101, v98
	v_fma_f32 v97, -v97, v100, v99
	v_div_fmas_f32 v97, v97, v98, v100
	v_div_fixup_f32 v198, v97, v96, 1.0
.LBB0_2242:
	s_or_b64 exec, exec, s[14:15]
	v_add_u32_e32 v96, 48, v195
	v_cmp_gt_u32_e32 vcc, s79, v96
	s_and_saveexec_b64 s[14:15], vcc
	s_cbranch_execz .LBB0_2244
	v_or_b32_e32 v96, s33, v96
	v_ashrrev_i32_e32 v97, 31, v96
	v_lshl_add_u64 v[96:97], v[96:97], 2, s[28:29]
	s_waitcnt vmcnt(0)
	v_mov_b32_e32 v96, v245
	v_fmamk_f32 v96, v96, 0x3a800000, v237
	v_sqrt_f32_e32 v97, v96
	s_nop 0
	v_add_u32_e32 v98, -1, v97
	v_add_u32_e32 v99, 1, v97
	v_fma_f32 v100, -v98, v97, v96
	v_fma_f32 v101, -v99, v97, v96
	v_cmp_ge_f32_e64 s[0:1], 0, v100
	s_nop 1
	v_cndmask_b32_e64 v97, v97, v98, s[0:1]
	v_cmp_lt_f32_e64 s[0:1], 0, v101
	s_nop 1
	v_cndmask_b32_e64 v97, v97, v99, s[0:1]
	v_mov_b32_e32 v96, v97
	v_div_scale_f32 v97, s[0:1], v96, v96, 1.0
	v_rcp_f32_e32 v98, v97
	v_div_scale_f32 v99, vcc, 1.0, v96, 1.0
	v_fma_f32 v100, -v97, v98, 1.0
	v_fmac_f32_e32 v98, v100, v98
	v_mul_f32_e32 v100, v99, v98
	v_fma_f32 v101, -v97, v100, v99
	v_fmac_f32_e32 v100, v101, v98
	v_fma_f32 v97, -v97, v100, v99
	v_div_fmas_f32 v97, v97, v98, v100
	v_div_fixup_f32 v128, v97, v96, 1.0
.LBB0_2244:
	s_or_b64 exec, exec, s[14:15]
	v_add_u32_e32 v241, 0x80, v195
	v_cmp_gt_u32_e32 vcc, s79, v241
	v_mov_b32_e32 v194, 0
	v_mov_b32_e32 v196, 0
	s_and_saveexec_b64 s[14:15], vcc
	s_cbranch_execz .LBB0_2246
	v_or_b32_e32 v96, s33, v241
	v_ashrrev_i32_e32 v97, 31, v96
	v_lshl_add_u64 v[96:97], v[96:97], 2, s[28:29]
	s_waitcnt vmcnt(0)
	v_mov_b32_e32 v96, v246
	v_fmamk_f32 v96, v96, 0x3a800000, v237
	v_sqrt_f32_e32 v97, v96
	s_nop 0
	v_add_u32_e32 v98, -1, v97
	v_add_u32_e32 v99, 1, v97
	v_fma_f32 v100, -v98, v97, v96
	v_fma_f32 v101, -v99, v97, v96
	v_cmp_ge_f32_e64 s[0:1], 0, v100
	s_nop 1
	v_cndmask_b32_e64 v97, v97, v98, s[0:1]
	v_cmp_lt_f32_e64 s[0:1], 0, v101
	s_nop 1
	v_cndmask_b32_e64 v97, v97, v99, s[0:1]
	v_mov_b32_e32 v96, v97
	v_div_scale_f32 v97, s[0:1], v96, v96, 1.0
	v_rcp_f32_e32 v98, v97
	v_div_scale_f32 v99, vcc, 1.0, v96, 1.0
	v_fma_f32 v100, -v97, v98, 1.0
	v_fmac_f32_e32 v98, v100, v98
	v_mul_f32_e32 v100, v99, v98
	v_fma_f32 v101, -v97, v100, v99
	v_fmac_f32_e32 v100, v101, v98
	v_fma_f32 v97, -v97, v100, v99
	v_div_fmas_f32 v97, v97, v98, v100
	v_div_fixup_f32 v196, v97, v96, 1.0
.LBB0_2246:
	s_or_b64 exec, exec, s[14:15]
	v_add_u32_e32 v240, 0x90, v195
	v_cmp_gt_u32_e32 vcc, s79, v240
	s_and_saveexec_b64 s[14:15], vcc
	s_cbranch_execz .LBB0_2248
	v_or_b32_e32 v96, s33, v240
	v_ashrrev_i32_e32 v97, 31, v96
	v_lshl_add_u64 v[96:97], v[96:97], 2, s[28:29]
	s_waitcnt vmcnt(0)
	v_mov_b32_e32 v96, v247
	v_fmamk_f32 v96, v96, 0x3a800000, v237
	v_sqrt_f32_e32 v97, v96
	s_nop 0
	v_add_u32_e32 v98, -1, v97
	v_add_u32_e32 v99, 1, v97
	v_fma_f32 v100, -v98, v97, v96
	v_fma_f32 v101, -v99, v97, v96
	v_cmp_ge_f32_e64 s[0:1], 0, v100
	s_nop 1
	v_cndmask_b32_e64 v97, v97, v98, s[0:1]
	v_cmp_lt_f32_e64 s[0:1], 0, v101
	s_nop 1
	v_cndmask_b32_e64 v97, v97, v99, s[0:1]
	v_mov_b32_e32 v96, v97
	v_div_scale_f32 v97, s[0:1], v96, v96, 1.0
	v_rcp_f32_e32 v98, v97
	v_div_scale_f32 v99, vcc, 1.0, v96, 1.0
	v_fma_f32 v100, -v97, v98, 1.0
	v_fmac_f32_e32 v98, v100, v98
	v_mul_f32_e32 v100, v99, v98
	v_fma_f32 v101, -v97, v100, v99
	v_fmac_f32_e32 v100, v101, v98
	v_fma_f32 v97, -v97, v100, v99
	v_div_fmas_f32 v97, v97, v98, v100
	v_div_fixup_f32 v194, v97, v96, 1.0
.LBB0_2248:
	s_or_b64 exec, exec, s[14:15]
	v_add_u32_e32 v203, 0xa0, v195
	v_cmp_gt_u32_e32 vcc, s79, v203
	v_mov_b32_e32 v130, 0
	v_mov_b32_e32 v192, 0
	s_and_saveexec_b64 s[14:15], vcc
	s_cbranch_execz .LBB0_2250
	v_or_b32_e32 v96, s33, v203
	v_ashrrev_i32_e32 v97, 31, v96
	v_lshl_add_u64 v[96:97], v[96:97], 2, s[28:29]
	s_waitcnt vmcnt(0)
	v_mov_b32_e32 v96, v250
	v_fmamk_f32 v96, v96, 0x3a800000, v237
	v_sqrt_f32_e32 v97, v96
	s_nop 0
	v_add_u32_e32 v98, -1, v97
	v_add_u32_e32 v99, 1, v97
	v_fma_f32 v100, -v98, v97, v96
	v_fma_f32 v101, -v99, v97, v96
	v_cmp_ge_f32_e64 s[0:1], 0, v100
	s_nop 1
	v_cndmask_b32_e64 v97, v97, v98, s[0:1]
	v_cmp_lt_f32_e64 s[0:1], 0, v101
	s_nop 1
	v_cndmask_b32_e64 v97, v97, v99, s[0:1]
	v_mov_b32_e32 v96, v97
	v_div_scale_f32 v97, s[0:1], v96, v96, 1.0
	v_rcp_f32_e32 v98, v97
	v_div_scale_f32 v99, vcc, 1.0, v96, 1.0
	v_fma_f32 v100, -v97, v98, 1.0
	v_fmac_f32_e32 v98, v100, v98
	v_mul_f32_e32 v100, v99, v98
	v_fma_f32 v101, -v97, v100, v99
	v_fmac_f32_e32 v100, v101, v98
	v_fma_f32 v97, -v97, v100, v99
	v_div_fmas_f32 v97, v97, v98, v100
	v_div_fixup_f32 v192, v97, v96, 1.0
.LBB0_2250:
	s_or_b64 exec, exec, s[14:15]
	v_add_u32_e32 v201, 0xb0, v195
	v_cmp_gt_u32_e32 vcc, s79, v201
	s_and_saveexec_b64 s[14:15], vcc
	s_cbranch_execz .LBB0_2252
	v_or_b32_e32 v96, s33, v201
	v_ashrrev_i32_e32 v97, 31, v96
	v_lshl_add_u64 v[96:97], v[96:97], 2, s[28:29]
	s_waitcnt vmcnt(0)
	v_mov_b32_e32 v96, v251
	v_fmamk_f32 v96, v96, 0x3a800000, v237
	v_sqrt_f32_e32 v97, v96
	s_nop 0
	v_add_u32_e32 v98, -1, v97
	v_add_u32_e32 v99, 1, v97
	v_fma_f32 v100, -v98, v97, v96
	v_fma_f32 v101, -v99, v97, v96
	v_cmp_ge_f32_e64 s[0:1], 0, v100
	s_nop 1
	v_cndmask_b32_e64 v97, v97, v98, s[0:1]
	v_cmp_lt_f32_e64 s[0:1], 0, v101
	s_nop 1
	v_cndmask_b32_e64 v97, v97, v99, s[0:1]
	v_mov_b32_e32 v96, v97
	v_div_scale_f32 v97, s[0:1], v96, v96, 1.0
	v_rcp_f32_e32 v98, v97
	v_div_scale_f32 v99, vcc, 1.0, v96, 1.0
	v_fma_f32 v100, -v97, v98, 1.0
	v_fmac_f32_e32 v98, v100, v98
	v_mul_f32_e32 v100, v99, v98
	v_fma_f32 v101, -v97, v100, v99
	v_fmac_f32_e32 v100, v101, v98
	v_fma_f32 v97, -v97, v100, v99
	v_div_fmas_f32 v97, v97, v98, v100
	v_div_fixup_f32 v130, v97, v96, 1.0
